# v35 plus fold row loop prefetching the next weight row
# baseline (speedup 1.0000x reference)
.LBB0_226:
	s_add_i32 s5, s9, s5
	s_min_i32 s6, s5, s4
	s_cmp_ge_i32 s8, s6
	s_mov_b32 s62, s26
	s_cbranch_scc1 .LBB0_218
	v_sub_u32_e32 v0, s0, v0
	v_ashrrev_i32_e32 v1, 31, v0
	v_lshlrev_b64 v[0:1], 13, v[0:1]
	v_lshl_add_u64 v[0:1], s[38:39], 0, v[0:1]
	s_lshl_b64 s[10:11], s[44:45], 13
	s_add_u32 s10, s46, s10
	v_readfirstlane_b32 s12, v0
	v_readfirstlane_b32 s13, v1
	s_addc_u32 s11, s47, s11
	v_lshl_add_u64 v[48:49], v[0:1], 0, v[84:85]
	s_nop 2
	global_load_dwordx4 v[0:3], v84, s[12:13]
	global_load_dwordx4 v[4:7], v84, s[12:13] offset:16
	global_load_dwordx4 v[8:11], v84, s[10:11]
	global_load_dwordx4 v[12:15], v84, s[10:11] offset:16
	global_load_dwordx4 v[16:19], v84, s[12:13] offset:2048
	global_load_dwordx4 v[20:23], v84, s[12:13] offset:2064
	global_load_dwordx4 v[24:27], v84, s[10:11] offset:2048
	global_load_dwordx4 v[28:31], v84, s[10:11] offset:2064
	v_add_co_u32_e32 v50, vcc, s17, v48
	v_lshl_add_u64 v[56:57], s[10:11], 0, v[84:85]
	s_mov_b64 s[10:11], 0x1000
	v_addc_co_u32_e32 v51, vcc, 0, v49, vcc
	v_lshl_add_u64 v[36:37], v[48:49], 0, s[10:11]
	v_lshl_add_u64 v[44:45], v[56:57], 0, s[10:11]
	v_add_co_u32_e32 v58, vcc, s17, v56
	s_mov_b64 s[10:11], 0x1800
	s_nop 0
	v_addc_co_u32_e32 v59, vcc, 0, v57, vcc
	v_lshl_add_u64 v[52:53], v[48:49], 0, s[10:11]
	v_lshl_add_u64 v[60:61], v[56:57], 0, s[10:11]
	global_load_dwordx4 v[32:35], v[50:51], off
	s_nop 0
	global_load_dwordx4 v[36:39], v[36:37], off offset:16
	s_nop 0
	global_load_dwordx4 v[40:43], v[58:59], off
	s_nop 0
	global_load_dwordx4 v[44:47], v[44:45], off offset:16
	s_nop 0
	global_load_dwordx4 v[48:51], v[50:51], off offset:2048
	s_nop 0
	global_load_dwordx4 v[52:55], v[52:53], off offset:16
	s_nop 0
	global_load_dwordx4 v[56:59], v[58:59], off offset:2048
	s_nop 0
	global_load_dwordx4 v[60:63], v[60:61], off offset:16
	s_lshl_b64 s[10:11], s[0:1], 17
	s_sub_i32 s7, s6, s9
	s_mul_hi_i32 s14, s34, s0
	s_mul_i32 s15, s34, s0
	s_sub_i32 s0, s8, s9
	s_add_u32 s12, s10, 0x18000000
	s_addc_u32 s13, s11, 0
	s_lshl_b32 s1, s42, 2
	s_or_b32 s8, s12, s1
	s_ashr_i32 s1, s0, 31
	s_lshl_b64 s[10:11], s[0:1], 2
	s_add_u32 s8, s8, s10
	s_addc_u32 s9, s13, s11
	s_lshl_b32 s16, s40, 2
	s_or_b32 s12, s12, s16
	s_add_u32 s10, s12, s10
	s_addc_u32 s11, s13, s11
	s_lshl_b64 s[12:13], s[0:1], 12
	s_add_u32 s1, s12, s15
	s_addc_u32 s13, s13, s14
	s_add_u32 s12, s1, s30
	s_addc_u32 s13, s13, s31
	v_lshl_add_u64 v[74:75], s[12:13], 0, v[72:73]
	s_mov_b64 s[100:101], 0x1000
	v_lshl_add_u64 v[106:107], s[20:21], 0, v[74:75]
	global_load_dwordx4 v[90:93], v[106:107], off
	global_load_dwordx4 v[94:97], v[106:107], off offset:1024
	global_load_dwordx4 v[98:101], v[106:107], off offset:2048
	global_load_dwordx4 v[102:105], v[106:107], off offset:3072
	s_branch .LBB0_229

.LBB0_229:
	s_waitcnt lgkmcnt(0)
	s_waitcnt vmcnt(0)
	v_mov_b32_e32 v76, v90
	v_mov_b32_e32 v77, v91
	v_mov_b32_e32 v78, v92
	v_mov_b32_e32 v79, v93
	v_mov_b32_e32 v80, v94
	v_mov_b32_e32 v81, v95
	v_mov_b32_e32 v82, v96
	v_mov_b32_e32 v83, v97
	v_mov_b32_e32 v68, v98
	v_mov_b32_e32 v69, v99
	v_mov_b32_e32 v70, v100
	v_mov_b32_e32 v71, v101
	v_mov_b32_e32 v64, v102
	v_mov_b32_e32 v65, v103
	v_mov_b32_e32 v66, v104
	v_mov_b32_e32 v67, v105
	v_lshl_add_u64 v[106:107], s[20:21], 0, v[74:75]
	v_lshl_add_u64 v[106:107], v[106:107], 0, s[100:101]
	global_load_dwordx4 v[90:93], v[106:107], off
	global_load_dwordx4 v[94:97], v[106:107], off offset:1024
	global_load_dwordx4 v[98:101], v[106:107], off offset:2048
	global_load_dwordx4 v[102:105], v[106:107], off offset:3072
	v_lshlrev_b32_e32 v86, 16, v76
	v_and_b32_e32 v76, 0xffff0000, v76
	v_mul_f32_e32 v87, v1, v76
	v_mul_f32_e32 v76, v9, v76
	v_fmac_f32_e32 v87, v0, v86
	v_fmac_f32_e32 v76, v8, v86
	v_lshlrev_b32_e32 v86, 16, v77
	v_and_b32_e32 v77, 0xffff0000, v77
	v_mul_f32_e32 v88, v3, v77
	v_mul_f32_e32 v77, v11, v77
	v_add_f32_e32 v76, 0, v76
	v_fmac_f32_e32 v77, v10, v86
	v_add_f32_e32 v76, v77, v76
	v_lshlrev_b32_e32 v77, 16, v78
	v_and_b32_e32 v78, 0xffff0000, v78
	v_fmac_f32_e32 v88, v2, v86
	v_mul_f32_e32 v86, v5, v78
	v_mul_f32_e32 v78, v13, v78
	v_fmac_f32_e32 v78, v12, v77
	v_add_f32_e32 v76, v78, v76
	v_and_b32_e32 v78, 0xffff0000, v79
	v_fmac_f32_e32 v86, v4, v77
	v_lshlrev_b32_e32 v77, 16, v79
	v_mul_f32_e32 v79, v7, v78
	v_mul_f32_e32 v78, v15, v78
	v_fmac_f32_e32 v78, v14, v77
	v_add_f32_e32 v87, 0, v87
	v_add_f32_e32 v76, v78, v76
	s_nop 0
	v_and_b32_e32 v78, 0xffff0000, v80
	v_add_f32_e32 v87, v88, v87
	v_fmac_f32_e32 v79, v6, v77
	v_lshlrev_b32_e32 v77, 16, v80
	v_mul_f32_e32 v80, v17, v78
	v_mul_f32_e32 v78, v25, v78
	v_add_f32_e32 v86, v86, v87
	v_fmac_f32_e32 v78, v24, v77
	v_add_f32_e32 v79, v79, v86
	v_fmac_f32_e32 v80, v16, v77
	v_add_f32_e32 v76, v78, v76
	v_and_b32_e32 v78, 0xffff0000, v81
	v_add_f32_e32 v79, v80, v79
	v_lshlrev_b32_e32 v77, 16, v81
	v_mul_f32_e32 v80, v19, v78
	v_mul_f32_e32 v78, v27, v78
	v_fmac_f32_e32 v78, v26, v77
	v_fmac_f32_e32 v80, v18, v77
	v_add_f32_e32 v76, v78, v76
	v_and_b32_e32 v78, 0xffff0000, v82
	v_add_f32_e32 v79, v80, v79
	v_lshlrev_b32_e32 v77, 16, v82
	v_mul_f32_e32 v80, v21, v78
	v_mul_f32_e32 v78, v29, v78
	v_fmac_f32_e32 v78, v28, v77
	v_fmac_f32_e32 v80, v20, v77
	v_add_f32_e32 v76, v78, v76
	v_and_b32_e32 v78, 0xffff0000, v83
	v_add_f32_e32 v79, v80, v79
	v_lshlrev_b32_e32 v77, 16, v83
	v_mul_f32_e32 v80, v23, v78
	v_mul_f32_e32 v78, v31, v78
	v_fmac_f32_e32 v80, v22, v77
	v_fmac_f32_e32 v78, v30, v77
	s_nop 0
	v_lshlrev_b32_e32 v77, 16, v68
	v_and_b32_e32 v68, 0xffff0000, v68
	v_add_f32_e32 v76, v78, v76
	v_mul_f32_e32 v78, v33, v68
	v_mul_f32_e32 v68, v41, v68
	v_fmac_f32_e32 v68, v40, v77
	v_add_f32_e32 v68, v68, v76
	v_lshlrev_b32_e32 v76, 16, v69
	v_and_b32_e32 v69, 0xffff0000, v69
	v_fmac_f32_e32 v78, v32, v77
	v_mul_f32_e32 v77, v35, v69
	v_mul_f32_e32 v69, v43, v69
	v_fmac_f32_e32 v69, v42, v76
	v_add_f32_e32 v68, v69, v68
	v_lshlrev_b32_e32 v69, 16, v70
	v_and_b32_e32 v70, 0xffff0000, v70
	v_fmac_f32_e32 v77, v34, v76
	v_mul_f32_e32 v76, v37, v70
	v_mul_f32_e32 v70, v45, v70
	v_fmac_f32_e32 v70, v44, v69
	v_add_f32_e32 v68, v70, v68
	v_and_b32_e32 v70, 0xffff0000, v71
	v_fmac_f32_e32 v76, v36, v69
	v_lshlrev_b32_e32 v69, 16, v71
	v_mul_f32_e32 v71, v39, v70
	v_mul_f32_e32 v70, v47, v70
	v_fmac_f32_e32 v71, v38, v69
	v_fmac_f32_e32 v70, v46, v69
	s_nop 0
	v_lshlrev_b32_e32 v69, 16, v64
	v_and_b32_e32 v64, 0xffff0000, v64
	v_add_f32_e32 v68, v70, v68
	v_mul_f32_e32 v70, v49, v64
	v_mul_f32_e32 v64, v57, v64
	v_fmac_f32_e32 v64, v56, v69
	v_add_f32_e32 v64, v64, v68
	v_lshlrev_b32_e32 v68, 16, v65
	v_and_b32_e32 v65, 0xffff0000, v65
	v_add_f32_e32 v79, v80, v79
	v_fmac_f32_e32 v70, v48, v69
	v_mul_f32_e32 v69, v51, v65
	v_mul_f32_e32 v65, v59, v65
	v_add_f32_e32 v78, v78, v79
	v_fmac_f32_e32 v65, v58, v68
	v_add_f32_e32 v77, v77, v78
	v_add_f32_e32 v64, v65, v64
	v_lshlrev_b32_e32 v65, 16, v66
	v_and_b32_e32 v66, 0xffff0000, v66
	v_add_f32_e32 v76, v76, v77
	v_fmac_f32_e32 v69, v50, v68
	v_mul_f32_e32 v68, v53, v66
	v_mul_f32_e32 v66, v61, v66
	v_add_f32_e32 v71, v71, v76
	v_fmac_f32_e32 v66, v60, v65
	v_add_f32_e32 v70, v70, v71
	v_add_f32_e32 v64, v66, v64
	v_and_b32_e32 v66, 0xffff0000, v67
	v_add_f32_e32 v69, v69, v70
	v_fmac_f32_e32 v68, v52, v65
	v_lshlrev_b32_e32 v65, 16, v67
	v_mul_f32_e32 v67, v55, v66
	v_add_f32_e32 v68, v68, v69
	v_fmac_f32_e32 v67, v54, v65
	v_mul_f32_e32 v66, v63, v66
	v_add_f32_e32 v67, v67, v68
	v_fmac_f32_e32 v66, v62, v65
	v_add_f32_e32 v66, v66, v64
	ds_bpermute_b32 v64, v117, v67
	s_waitcnt lgkmcnt(0)
	v_add_f32_e32 v64, v67, v64
	ds_bpermute_b32 v67, v117, v66
	ds_bpermute_b32 v65, v119, v64
	s_waitcnt lgkmcnt(1)
	v_add_f32_e32 v66, v66, v67
	ds_bpermute_b32 v67, v119, v66
	s_waitcnt lgkmcnt(1)
	v_add_f32_e32 v64, v64, v65
	ds_bpermute_b32 v65, v121, v64
	s_waitcnt lgkmcnt(1)
	v_add_f32_e32 v66, v66, v67
	ds_bpermute_b32 v67, v121, v66
	s_waitcnt lgkmcnt(1)
	v_add_f32_e32 v64, v64, v65
	ds_bpermute_b32 v65, v123, v64
	s_waitcnt lgkmcnt(1)
	v_add_f32_e32 v66, v66, v67
	ds_bpermute_b32 v67, v123, v66
	s_waitcnt lgkmcnt(1)
	v_add_f32_e32 v64, v64, v65
	ds_bpermute_b32 v65, v131, v64
	s_waitcnt lgkmcnt(1)
	v_add_f32_e32 v66, v66, v67
	ds_bpermute_b32 v67, v131, v66
	s_waitcnt lgkmcnt(1)
	v_add_f32_e32 v64, v64, v65
	ds_bpermute_b32 v65, v133, v64
	s_waitcnt lgkmcnt(1)
	v_add_f32_e32 v66, v66, v67
	ds_bpermute_b32 v67, v133, v66
	s_and_saveexec_b64 s[30:31], s[36:37]
	s_cbranch_execz .LBB0_228
	s_add_u32 s12, s20, s10
	s_addc_u32 s13, s21, s11
	s_add_u32 s14, s20, s8
	s_addc_u32 s15, s21, s9
	s_waitcnt lgkmcnt(1)
	v_add_f32_e32 v64, v64, v65
	s_waitcnt lgkmcnt(0)
	v_add_f32_e32 v66, v66, v67
	global_store_dword v85, v64, s[14:15]
	global_store_dword v85, v66, s[12:13]
	s_branch .LBB0_228
